# gate math stages with no MFMA in flight use packed f32 ops (pk_add / pk_fma / pk_mul on adjacent elements)
# speedup vs baseline: 1.0103x; 1.0103x over previous
; #define LAS __attribute__((address_space(3)))
; template <int dir>
; __device__ __forceinline__ void lru_pass(LAS unsigned char* lds, const Params& P, int b, int h, int q, bool dry) {
;     ...
;             const int sbase = 32 * wid + 16 * g;
;             { const int sl = 32 * wid + s_i; const int tlA = dir == 0 ? sl : 255 - sl;
;               const LAS unsigned char* ap = XC + tlA * XC_PITCH + 16 * g;
;               const LAS unsigned char* wrp = WB + nl * XC_PITCH + 16 * g; const LAS unsigned char* wip = wrp + 32 * XC_PITCH;
; #pragma unroll
;               for (int ks = 0; ks < 8; ++ks) { const bf16x8 A = *(const LAS bf16x8*)(ap + 32 * ks);
;                   const bf16x8 Br = *(const LAS bf16x8*)(wrp + 32 * ks), Bi = *(const LAS bf16x8*)(wip + 32 * ks);
;                   zr = __builtin_amdgcn_mfma_f32_32x32x16_bf16(A, Br, zr, 0, 0, 0); zi = __builtin_amdgcn_mfma_f32_32x32x16_bf16(A, Bi, zi, 0, 0, 0); } }
;             unsigned xcb[16], pk[16];
; #pragma unroll
;             for (int v = 0; v < 16; ++v) { const int s = sbase + v; const int tl = dir == 0 ? s : 255 - s; xcb[v] = *(const LAS bf16_t*)(XC + tl * XC_PITCH + chl * 2);
;                 if (dir == 0) pk[v] = *(const LAS bf16_t*)(TIN + tl * IO_NP + nl * 2); else pk[v] = *(const LAS unsigned*)(TIN + tl * IO_WP + nl * 4); }
;             float Pp = 1.f, E = 0.f;
; #pragma unroll
;             for (int v = 0; v < 16; ++v) {
;                 const float xcv = __uint_as_float(xcb[v] << 16);
;                 const float r = __builtin_amdgcn_rcpf(1.0f + __builtin_amdgcn_exp2f(zr[v]));
;                 const float ig = __builtin_amdgcn_rcpf(1.0f + __builtin_amdgcn_exp2f(zi[v]));
;                 const float a = __builtin_amdgcn_exp2f(cl * r);
;                 const float sq = __builtin_amdgcn_sqrtf(fmaf(-a, a, 1.0f));
;                 const float u = sq * ig * xcv;
;                 E = fmaf(a, E, u); Pp *= a; zr[v] = E; zi[v] = Pp; }
.Llruf_wres:
	ds_read_b128 v[120:123], v160
	ds_read_b128 v[124:127], v160 offset:32
	ds_read_b128 v[168:171], v160 offset:64
	ds_read_b128 v[172:175], v160 offset:96
	ds_read_b128 v[176:179], v160 offset:128
	ds_read_b128 v[180:183], v160 offset:160
	ds_read_b128 v[184:187], v160 offset:192
	ds_read_b128 v[188:191], v160 offset:224
	ds_read_b128 v[236:239], v161 offset:8704
	ds_read_b128 v[240:243], v161 offset:8736
	ds_read_b128 v[244:247], v161 offset:8768
	ds_read_b128 v[248:251], v161 offset:8800
	s_waitcnt lgkmcnt(11)
	v_mfma_f32_32x32x16_bf16 v[32:47], v[120:123], v[204:207], v[0:15]
	s_waitcnt lgkmcnt(10)
	v_mfma_f32_32x32x16_bf16 v[32:47], v[124:127], v[208:211], v[32:47]
	s_waitcnt lgkmcnt(9)
	v_mfma_f32_32x32x16_bf16 v[32:47], v[168:171], v[212:215], v[32:47]
	s_waitcnt lgkmcnt(8)
	v_mfma_f32_32x32x16_bf16 v[32:47], v[172:175], v[216:219], v[32:47]
	s_waitcnt lgkmcnt(7)
	v_mfma_f32_32x32x16_bf16 v[32:47], v[176:179], v[220:223], v[32:47]
	s_waitcnt lgkmcnt(6)
	v_mfma_f32_32x32x16_bf16 v[32:47], v[180:183], v[224:227], v[32:47]
	s_waitcnt lgkmcnt(5)
	v_mfma_f32_32x32x16_bf16 v[32:47], v[184:187], v[228:231], v[32:47]
	s_waitcnt lgkmcnt(4)
	v_mfma_f32_32x32x16_bf16 v[32:47], v[188:191], v[232:235], v[32:47]
	s_waitcnt lgkmcnt(3)
	v_mfma_f32_32x32x16_bf16 v[48:63], v[120:123], v[236:239], v[16:31]
	ds_read_b128 v[236:239], v161 offset:8832
	s_nop 9
	v_exp_f32_e32 v32, v32
	v_exp_f32_e32 v33, v33
	v_exp_f32_e32 v34, v34
	v_exp_f32_e32 v35, v35
	v_exp_f32_e32 v36, v36
	v_exp_f32_e32 v37, v37
	v_exp_f32_e32 v38, v38
	v_exp_f32_e32 v39, v39
	s_waitcnt lgkmcnt(3)
	v_mfma_f32_32x32x16_bf16 v[48:63], v[124:127], v[240:243], v[48:63]
	ds_read_b128 v[240:243], v161 offset:8864
	v_exp_f32_e32 v40, v40
	v_exp_f32_e32 v41, v41
	v_exp_f32_e32 v42, v42
	v_exp_f32_e32 v43, v43
	v_exp_f32_e32 v44, v44
	v_exp_f32_e32 v45, v45
	v_exp_f32_e32 v46, v46
	v_exp_f32_e32 v47, v47
	s_waitcnt lgkmcnt(3)
	v_mfma_f32_32x32x16_bf16 v[48:63], v[168:171], v[244:247], v[48:63]
	ds_read_b128 v[244:247], v161 offset:8896
	v_fma_f32 v32, v32, v138, v138
	v_fma_f32 v33, v33, v138, v138
	v_fma_f32 v34, v34, v138, v138
	v_fma_f32 v35, v35, v138, v138
	v_fma_f32 v36, v36, v138, v138
	v_fma_f32 v37, v37, v138, v138
	v_fma_f32 v38, v38, v138, v138
	v_fma_f32 v39, v39, v138, v138
	s_waitcnt lgkmcnt(3)
	v_mfma_f32_32x32x16_bf16 v[48:63], v[172:175], v[248:251], v[48:63]
	ds_read_b128 v[248:251], v161 offset:8928
	v_fma_f32 v40, v40, v138, v138
	v_fma_f32 v41, v41, v138, v138
	v_fma_f32 v42, v42, v138, v138
	v_fma_f32 v43, v43, v138, v138
	v_fma_f32 v44, v44, v138, v138
	v_fma_f32 v45, v45, v138, v138
	v_fma_f32 v46, v46, v138, v138
	v_fma_f32 v47, v47, v138, v138
	s_waitcnt lgkmcnt(3)
	v_mfma_f32_32x32x16_bf16 v[48:63], v[176:179], v[236:239], v[48:63]
	v_rcp_f32_e32 v32, v32
	v_rcp_f32_e32 v33, v33
	v_rcp_f32_e32 v34, v34
	v_rcp_f32_e32 v35, v35
	v_rcp_f32_e32 v36, v36
	v_rcp_f32_e32 v37, v37
	v_rcp_f32_e32 v38, v38
	v_rcp_f32_e32 v39, v39
	s_waitcnt lgkmcnt(2)
	v_mfma_f32_32x32x16_bf16 v[48:63], v[180:183], v[240:243], v[48:63]
	v_rcp_f32_e32 v40, v40
	v_rcp_f32_e32 v41, v41
	v_rcp_f32_e32 v42, v42
	v_rcp_f32_e32 v43, v43
	v_rcp_f32_e32 v44, v44
	v_rcp_f32_e32 v45, v45
	v_rcp_f32_e32 v46, v46
	v_rcp_f32_e32 v47, v47
	s_waitcnt lgkmcnt(1)
	v_mfma_f32_32x32x16_bf16 v[48:63], v[184:187], v[244:247], v[48:63]
	v_exp_f32_e32 v32, v32
	v_exp_f32_e32 v33, v33
	v_exp_f32_e32 v34, v34
	v_exp_f32_e32 v35, v35
	v_exp_f32_e32 v36, v36
	v_exp_f32_e32 v37, v37
	v_exp_f32_e32 v38, v38
	v_exp_f32_e32 v39, v39
	s_waitcnt lgkmcnt(0)
	v_mfma_f32_32x32x16_bf16 v[48:63], v[188:191], v[248:251], v[48:63]
	v_exp_f32_e32 v40, v40
	v_exp_f32_e32 v41, v41
	v_exp_f32_e32 v42, v42
	v_exp_f32_e32 v43, v43
	v_exp_f32_e32 v44, v44
	v_exp_f32_e32 v45, v45
	v_exp_f32_e32 v46, v46
	v_exp_f32_e32 v47, v47
	ds_read_u16 v152, v162
	ds_read_u16 v154, v162 offset:272
	ds_read_u16 v155, v162 offset:544
	ds_read_u16 v157, v162 offset:816
	ds_read_u16 v196, v162 offset:1088
	ds_read_u16 v197, v162 offset:1360
	ds_read_u16 v177, v162 offset:1632
	ds_read_u16 v178, v162 offset:1904
	ds_read_u16 v179, v162 offset:2176
	ds_read_u16 v180, v162 offset:2448
	ds_read_u16 v181, v162 offset:2720
	ds_read_u16 v182, v162 offset:2992
	ds_read_u16 v183, v162 offset:3264
	ds_read_u16 v184, v162 offset:3536
	ds_read_u16 v185, v162 offset:3808
	ds_read_u16 v187, v162 offset:4080
	v_exp_f32_e32 v48, v48
	v_exp_f32_e32 v49, v49
	v_exp_f32_e32 v50, v50
	v_exp_f32_e32 v51, v51
	v_exp_f32_e32 v52, v52
	v_exp_f32_e32 v53, v53
	v_exp_f32_e32 v54, v54
	v_exp_f32_e32 v55, v55
	v_exp_f32_e32 v56, v56
	v_exp_f32_e32 v57, v57
	v_exp_f32_e32 v58, v58
	v_exp_f32_e32 v59, v59
	v_exp_f32_e32 v60, v60
	v_exp_f32_e32 v61, v61
	v_exp_f32_e32 v62, v62
	v_exp_f32_e32 v63, v63
	v_pk_add_f32 v[48:49], v[48:49], 1.0 op_sel_hi:[1,0]
	v_pk_add_f32 v[50:51], v[50:51], 1.0 op_sel_hi:[1,0]
	v_pk_add_f32 v[52:53], v[52:53], 1.0 op_sel_hi:[1,0]
	v_pk_add_f32 v[54:55], v[54:55], 1.0 op_sel_hi:[1,0]
	v_pk_add_f32 v[56:57], v[56:57], 1.0 op_sel_hi:[1,0]
	v_pk_add_f32 v[58:59], v[58:59], 1.0 op_sel_hi:[1,0]
	v_pk_add_f32 v[60:61], v[60:61], 1.0 op_sel_hi:[1,0]
	v_pk_add_f32 v[62:63], v[62:63], 1.0 op_sel_hi:[1,0]
	v_rcp_f32_e32 v48, v48
	v_rcp_f32_e32 v49, v49
	v_rcp_f32_e32 v50, v50
	v_rcp_f32_e32 v51, v51
	v_rcp_f32_e32 v52, v52
	v_rcp_f32_e32 v53, v53
	v_rcp_f32_e32 v54, v54
	v_rcp_f32_e32 v55, v55
	v_rcp_f32_e32 v56, v56
	v_rcp_f32_e32 v57, v57
	v_rcp_f32_e32 v58, v58
	v_rcp_f32_e32 v59, v59
	v_rcp_f32_e32 v60, v60
	v_rcp_f32_e32 v61, v61
	v_rcp_f32_e32 v62, v62
	v_rcp_f32_e32 v63, v63
	s_waitcnt lgkmcnt(0)
; template <int dir>
; __device__ __forceinline__ void lru_pass(LAS unsigned char* lds, const Params& P, int b, int h, int q, bool dry) {
;     ...
;             for (int v = 0; v < 16; ++v) {
;                 const float xcv = __uint_as_float(xcb[v] << 16);
;                 const float r = __builtin_amdgcn_rcpf(1.0f + __builtin_amdgcn_exp2f(zr[v]));
;                 const float ig = __builtin_amdgcn_rcpf(1.0f + __builtin_amdgcn_exp2f(zi[v]));
;                 const float a = __builtin_amdgcn_exp2f(cl * r);
;                 const float sq = __builtin_amdgcn_sqrtf(fmaf(-a, a, 1.0f));
;                 const float u = sq * ig * xcv;
;                 E = fmaf(a, E, u); Pp *= a; zr[v] = E; zi[v] = Pp; }
;             const float Po = __shfl_xor(Pp, 32), Eo = __shfl_xor(E, 32);
;             const float P0 = g ? Po : Pp, E0 = g ? Eo : E, P1 = g ? Pp : Po, E1 = g ? E : Eo;
;             if (g == 0) { AGG[(wid * 2 + 0) * 32 + nl] = P0 * P1; AGG[(wid * 2 + 1) * 32 + nl] = fmaf(P1, E0, E1); }
	v_pk_fma_f32 v[120:121], v[32:33], v[32:33], 1.0 op_sel_hi:[1,1,0] neg_lo:[1,0,0] neg_hi:[1,0,0]
	v_pk_fma_f32 v[122:123], v[34:35], v[34:35], 1.0 op_sel_hi:[1,1,0] neg_lo:[1,0,0] neg_hi:[1,0,0]
	v_sqrt_f32_e32 v120, v120
	v_sqrt_f32_e32 v121, v121
	v_sqrt_f32_e32 v122, v122
	v_sqrt_f32_e32 v123, v123
	v_lshlrev_b32_e32 v152, 16, v152
	v_lshlrev_b32_e32 v154, 16, v154
	v_lshlrev_b32_e32 v155, 16, v155
	v_lshlrev_b32_e32 v157, 16, v157
	v_pk_mul_f32 v[120:121], v[120:121], v[48:49]
	v_pk_mul_f32 v[122:123], v[122:123], v[50:51]
	v_mul_f32_e32 v49, v120, v152
	v_mul_f32_e32 v172, v121, v154
	v_mul_f32_e32 v173, v122, v155
	v_mul_f32_e32 v174, v123, v157
	v_pk_fma_f32 v[120:121], v[36:37], v[36:37], 1.0 op_sel_hi:[1,1,0] neg_lo:[1,0,0] neg_hi:[1,0,0]
	v_pk_fma_f32 v[122:123], v[38:39], v[38:39], 1.0 op_sel_hi:[1,1,0] neg_lo:[1,0,0] neg_hi:[1,0,0]
	v_sqrt_f32_e32 v120, v120
	v_sqrt_f32_e32 v121, v121
	v_sqrt_f32_e32 v122, v122
	v_sqrt_f32_e32 v123, v123
	v_lshlrev_b32_e32 v196, 16, v196
	v_lshlrev_b32_e32 v197, 16, v197
	v_lshlrev_b32_e32 v177, 16, v177
	v_lshlrev_b32_e32 v178, 16, v178
	v_pk_mul_f32 v[120:121], v[120:121], v[52:53]
	v_pk_mul_f32 v[122:123], v[122:123], v[54:55]
	v_mul_f32_e32 v175, v120, v196
	v_mul_f32_e32 v176, v121, v197
	v_mul_f32_e32 v177, v122, v177
	v_mul_f32_e32 v178, v123, v178
	v_pk_fma_f32 v[120:121], v[40:41], v[40:41], 1.0 op_sel_hi:[1,1,0] neg_lo:[1,0,0] neg_hi:[1,0,0]
	v_pk_fma_f32 v[122:123], v[42:43], v[42:43], 1.0 op_sel_hi:[1,1,0] neg_lo:[1,0,0] neg_hi:[1,0,0]
	v_sqrt_f32_e32 v120, v120
	v_sqrt_f32_e32 v121, v121
	v_sqrt_f32_e32 v122, v122
	v_sqrt_f32_e32 v123, v123
	v_lshlrev_b32_e32 v179, 16, v179
	v_lshlrev_b32_e32 v180, 16, v180
	v_lshlrev_b32_e32 v181, 16, v181
	v_lshlrev_b32_e32 v182, 16, v182
	v_pk_mul_f32 v[120:121], v[120:121], v[56:57]
	v_pk_mul_f32 v[122:123], v[122:123], v[58:59]
	v_mul_f32_e32 v179, v120, v179
	v_mul_f32_e32 v180, v121, v180
	v_mul_f32_e32 v181, v122, v181
	v_mul_f32_e32 v182, v123, v182
	v_pk_fma_f32 v[120:121], v[44:45], v[44:45], 1.0 op_sel_hi:[1,1,0] neg_lo:[1,0,0] neg_hi:[1,0,0]
	v_pk_fma_f32 v[122:123], v[46:47], v[46:47], 1.0 op_sel_hi:[1,1,0] neg_lo:[1,0,0] neg_hi:[1,0,0]
	v_sqrt_f32_e32 v120, v120
	v_sqrt_f32_e32 v121, v121
	v_sqrt_f32_e32 v122, v122
	v_sqrt_f32_e32 v123, v123
	v_lshlrev_b32_e32 v183, 16, v183
	v_lshlrev_b32_e32 v184, 16, v184
	v_lshlrev_b32_e32 v185, 16, v185
	v_lshlrev_b32_e32 v187, 16, v187
	v_pk_mul_f32 v[120:121], v[120:121], v[60:61]
	v_pk_mul_f32 v[122:123], v[122:123], v[62:63]
	v_mul_f32_e32 v183, v120, v183
	v_mul_f32_e32 v184, v121, v184
	v_mul_f32_e32 v63, v122, v185
	v_mul_f32_e32 v185, v123, v187
	v_mov_b32_e32 v171, v32
	v_fmac_f32_e32 v49, 0, v32
	v_fmac_f32_e32 v172, v33, v49
	v_mul_f32_e32 v50, v171, v33
	v_fmac_f32_e32 v173, v34, v172
	v_mul_f32_e32 v51, v50, v34
	v_fmac_f32_e32 v174, v35, v173
	v_mul_f32_e32 v52, v51, v35
	v_fmac_f32_e32 v175, v36, v174
	v_mul_f32_e32 v53, v52, v36
	v_fmac_f32_e32 v176, v37, v175
	v_mul_f32_e32 v54, v53, v37
	v_fmac_f32_e32 v177, v38, v176
	v_mul_f32_e32 v55, v54, v38
	v_fmac_f32_e32 v178, v39, v177
	v_mul_f32_e32 v56, v55, v39
	v_fmac_f32_e32 v179, v40, v178
	v_mul_f32_e32 v57, v56, v40
	v_fmac_f32_e32 v180, v41, v179
	v_mul_f32_e32 v58, v57, v41
	v_fmac_f32_e32 v181, v42, v180
	v_mul_f32_e32 v59, v58, v42
	v_fmac_f32_e32 v182, v43, v181
	v_mul_f32_e32 v60, v59, v43
	v_fmac_f32_e32 v183, v44, v182
	v_mul_f32_e32 v61, v60, v44
	v_fmac_f32_e32 v184, v45, v183
	v_mul_f32_e32 v62, v61, v45
	v_fmac_f32_e32 v63, v46, v184
	v_mul_f32_e32 v186, v62, v46
	v_fmac_f32_e32 v185, v47, v63
	v_mul_f32_e32 v187, v186, v47
	v_mov_b32_e32 v188, v187
	v_mov_b32_e32 v252, v187
	v_mov_b32_e32 v189, v185
	v_mov_b32_e32 v253, v185
	s_nop 1
	v_permlane32_swap_b32 v188, v252
	v_permlane32_swap_b32 v189, v253
	s_and_saveexec_b64 s[18:19], vcc
	s_cbranch_execz .LBB0_299
	v_fma_f32 v32, v252, v189, v253
	v_mul_f32_e32 v33, v188, v252
	v_add_u32_e32 v35, s98, v147
	ds_write2_b32 v35, v33, v32 offset1:32

; #define LAS __attribute__((address_space(3)))
; template <int dir>
; __device__ __forceinline__ void lru_pass(LAS unsigned char* lds, const Params& P, int b, int h, int q, bool dry) {
;     ...
;             const int sbase = 32 * wid + 16 * g;
;             { const int sl = 32 * wid + s_i; const int tlA = dir == 0 ? sl : 255 - sl;
;               const LAS unsigned char* ap = XC + tlA * XC_PITCH + 16 * g;
;               const LAS unsigned char* wrp = WB + nl * XC_PITCH + 16 * g; const LAS unsigned char* wip = wrp + 32 * XC_PITCH;
; #pragma unroll
;               for (int ks = 0; ks < 8; ++ks) { const bf16x8 A = *(const LAS bf16x8*)(ap + 32 * ks);
;                   const bf16x8 Br = *(const LAS bf16x8*)(wrp + 32 * ks), Bi = *(const LAS bf16x8*)(wip + 32 * ks);
;                   zr = __builtin_amdgcn_mfma_f32_32x32x16_bf16(A, Br, zr, 0, 0, 0); zi = __builtin_amdgcn_mfma_f32_32x32x16_bf16(A, Bi, zi, 0, 0, 0); } }
;             unsigned xcb[16], pk[16];
; #pragma unroll
;             for (int v = 0; v < 16; ++v) { const int s = sbase + v; const int tl = dir == 0 ? s : 255 - s; xcb[v] = *(const LAS bf16_t*)(XC + tl * XC_PITCH + chl * 2);
;                 if (dir == 0) pk[v] = *(const LAS bf16_t*)(TIN + tl * IO_NP + nl * 2); else pk[v] = *(const LAS unsigned*)(TIN + tl * IO_WP + nl * 4); }
;             float Pp = 1.f, E = 0.f;
; #pragma unroll
;             for (int v = 0; v < 16; ++v) {
;                 const float xcv = __uint_as_float(xcb[v] << 16);
;                 const float r = __builtin_amdgcn_rcpf(1.0f + __builtin_amdgcn_exp2f(zr[v]));
;                 const float ig = __builtin_amdgcn_rcpf(1.0f + __builtin_amdgcn_exp2f(zi[v]));
;                 const float a = __builtin_amdgcn_exp2f(cl * r);
;                 const float sq = __builtin_amdgcn_sqrtf(fmaf(-a, a, 1.0f));
;                 const float u = sq * ig * xcv;
;                 E = fmaf(a, E, u); Pp *= a; zr[v] = E; zi[v] = Pp; }
.LBB0_311:
	ds_read_b128 v[128:131], v172
	ds_read_b128 v[48:51], v173
	ds_read_b128 v[132:135], v172 offset:32
	ds_read_b128 v[52:55], v173 offset:32
	ds_read_b128 v[224:227], v172 offset:64
	ds_read_b128 v[56:59], v173 offset:64
	ds_read_b128 v[228:231], v172 offset:96
	ds_read_b128 v[60:63], v173 offset:96
	ds_read_b128 v[232:235], v172 offset:128
	ds_read_b128 v[236:239], v172 offset:160
	ds_read_b128 v[240:243], v172 offset:192
	ds_read_b128 v[244:247], v172 offset:224
	ds_read_b128 v[248:251], v173 offset:8704
	ds_read_b128 v[146:149], v173 offset:8736
	s_waitcnt lgkmcnt(12)
	v_mfma_f32_32x32x16_bf16 v[32:47], v[128:131], v[48:51], v[0:15]
	ds_read_b128 v[48:51], v173 offset:128
	s_waitcnt lgkmcnt(11)
	v_mfma_f32_32x32x16_bf16 v[32:47], v[132:135], v[52:55], v[32:47]
	ds_read_b128 v[52:55], v173 offset:160
	s_waitcnt lgkmcnt(10)
	v_mfma_f32_32x32x16_bf16 v[32:47], v[224:227], v[56:59], v[32:47]
	ds_read_b128 v[56:59], v173 offset:192
	s_waitcnt lgkmcnt(9)
	v_mfma_f32_32x32x16_bf16 v[32:47], v[228:231], v[60:63], v[32:47]
	ds_read_b128 v[60:63], v173 offset:224
	s_waitcnt lgkmcnt(3)
	v_mfma_f32_32x32x16_bf16 v[32:47], v[232:235], v[48:51], v[32:47]
	s_waitcnt lgkmcnt(2)
	v_mfma_f32_32x32x16_bf16 v[32:47], v[236:239], v[52:55], v[32:47]
	s_waitcnt lgkmcnt(1)
	v_mfma_f32_32x32x16_bf16 v[32:47], v[240:243], v[56:59], v[32:47]
	s_waitcnt lgkmcnt(0)
	v_mfma_f32_32x32x16_bf16 v[32:47], v[244:247], v[60:63], v[32:47]
	v_mfma_f32_32x32x16_bf16 v[48:63], v[128:131], v[248:251], v[16:31]
	ds_read_b128 v[128:131], v173 offset:8768
	s_nop 9
	v_exp_f32_e32 v32, v32
	v_exp_f32_e32 v33, v33
	v_exp_f32_e32 v34, v34
	v_exp_f32_e32 v35, v35
	v_exp_f32_e32 v36, v36
	v_exp_f32_e32 v37, v37
	v_exp_f32_e32 v38, v38
	v_exp_f32_e32 v39, v39
	v_mfma_f32_32x32x16_bf16 v[48:63], v[132:135], v[146:149], v[48:63]
	ds_read_b128 v[132:135], v173 offset:8800
	v_exp_f32_e32 v40, v40
	v_exp_f32_e32 v41, v41
	v_exp_f32_e32 v42, v42
	v_exp_f32_e32 v43, v43
	v_exp_f32_e32 v44, v44
	v_exp_f32_e32 v45, v45
	v_exp_f32_e32 v46, v46
	v_exp_f32_e32 v47, v47
	s_waitcnt lgkmcnt(1)
	v_mfma_f32_32x32x16_bf16 v[48:63], v[224:227], v[128:131], v[48:63]
	ds_read_b128 v[224:227], v173 offset:8832
	v_fma_f32 v32, v32, v159, v159
	v_fma_f32 v33, v33, v159, v159
	v_fma_f32 v34, v34, v159, v159
	v_fma_f32 v35, v35, v159, v159
	v_fma_f32 v36, v36, v159, v159
	v_fma_f32 v37, v37, v159, v159
	v_fma_f32 v38, v38, v159, v159
	v_fma_f32 v39, v39, v159, v159
	s_waitcnt lgkmcnt(1)
	v_mfma_f32_32x32x16_bf16 v[48:63], v[228:231], v[132:135], v[48:63]
	ds_read_b128 v[228:231], v173 offset:8864
	v_fma_f32 v40, v40, v159, v159
	v_fma_f32 v41, v41, v159, v159
	v_fma_f32 v42, v42, v159, v159
	v_fma_f32 v43, v43, v159, v159
	v_fma_f32 v44, v44, v159, v159
	v_fma_f32 v45, v45, v159, v159
	v_fma_f32 v46, v46, v159, v159
	v_fma_f32 v47, v47, v159, v159
	s_waitcnt lgkmcnt(1)
	v_mfma_f32_32x32x16_bf16 v[48:63], v[232:235], v[224:227], v[48:63]
	ds_read_b128 v[128:131], v173 offset:8896
	v_rcp_f32_e32 v32, v32
	v_rcp_f32_e32 v33, v33
	v_rcp_f32_e32 v34, v34
	v_rcp_f32_e32 v35, v35
	v_rcp_f32_e32 v36, v36
	v_rcp_f32_e32 v37, v37
	v_rcp_f32_e32 v38, v38
	v_rcp_f32_e32 v39, v39
	s_waitcnt lgkmcnt(1)
	v_mfma_f32_32x32x16_bf16 v[48:63], v[236:239], v[228:231], v[48:63]
	ds_read_b128 v[132:135], v173 offset:8928
	v_rcp_f32_e32 v40, v40
	v_rcp_f32_e32 v41, v41
	v_rcp_f32_e32 v42, v42
	v_rcp_f32_e32 v43, v43
	v_rcp_f32_e32 v44, v44
	v_rcp_f32_e32 v45, v45
	v_rcp_f32_e32 v46, v46
	v_rcp_f32_e32 v47, v47
	s_waitcnt lgkmcnt(1)
	v_mfma_f32_32x32x16_bf16 v[48:63], v[240:243], v[128:131], v[48:63]
	v_exp_f32_e32 v32, v32
	v_exp_f32_e32 v33, v33
	v_exp_f32_e32 v34, v34
	v_exp_f32_e32 v35, v35
	v_exp_f32_e32 v36, v36
	v_exp_f32_e32 v37, v37
	v_exp_f32_e32 v38, v38
	v_exp_f32_e32 v39, v39
	s_waitcnt lgkmcnt(0)
	v_mfma_f32_32x32x16_bf16 v[48:63], v[244:247], v[132:135], v[48:63]
	v_exp_f32_e32 v40, v40
	v_exp_f32_e32 v41, v41
	v_exp_f32_e32 v42, v42
	v_exp_f32_e32 v43, v43
	v_exp_f32_e32 v44, v44
	v_exp_f32_e32 v45, v45
	v_exp_f32_e32 v46, v46
	v_exp_f32_e32 v47, v47
	ds_read_u16 v162, v174
	ds_read_b32 v226, v175
	ds_read_u16 v163, v176
	ds_read_b32 v225, v177
	ds_read_u16 v232, v178
	ds_read_b32 v224, v179
	ds_read_u16 v233, v180
	ds_read_b32 v223, v181
	ds_read_u16 v234, v182
	ds_read_b32 v135, v183
	ds_read_u16 v235, v184
	ds_read_b32 v134, v185
	ds_read_u16 v236, v186
	ds_read_b32 v133, v187
	ds_read_u16 v237, v188
	ds_read_b32 v131, v189
	ds_read_u16 v146, v190
	ds_read_b32 v132, v191
	ds_read_u16 v147, v192
	ds_read_b32 v130, v193
	ds_read_u16 v148, v194
	ds_read_b32 v129, v195
	ds_read_u16 v149, v196
	ds_read_b32 v128, v197
	ds_read_u16 v239, v198
	ds_read_b32 v67, v199
	ds_read_u16 v240, v200
	ds_read_b32 v66, v201
	ds_read_u16 v241, v202
	ds_read_b32 v64, v203
	ds_read_u16 v242, v204
	ds_read_b32 v251, v205
	v_exp_f32_e32 v48, v48
	v_exp_f32_e32 v49, v49
	v_exp_f32_e32 v50, v50
	v_exp_f32_e32 v51, v51
	v_exp_f32_e32 v52, v52
	v_exp_f32_e32 v53, v53
	v_exp_f32_e32 v54, v54
	v_exp_f32_e32 v55, v55
	v_exp_f32_e32 v56, v56
	v_exp_f32_e32 v57, v57
	v_exp_f32_e32 v58, v58
	v_exp_f32_e32 v59, v59
	v_exp_f32_e32 v60, v60
	v_exp_f32_e32 v61, v61
	v_exp_f32_e32 v62, v62
	v_exp_f32_e32 v63, v63
	v_pk_add_f32 v[48:49], v[48:49], 1.0 op_sel_hi:[1,0]
	v_pk_add_f32 v[50:51], v[50:51], 1.0 op_sel_hi:[1,0]
	v_pk_add_f32 v[52:53], v[52:53], 1.0 op_sel_hi:[1,0]
	v_pk_add_f32 v[54:55], v[54:55], 1.0 op_sel_hi:[1,0]
	v_pk_add_f32 v[56:57], v[56:57], 1.0 op_sel_hi:[1,0]
	v_pk_add_f32 v[58:59], v[58:59], 1.0 op_sel_hi:[1,0]
	v_pk_add_f32 v[60:61], v[60:61], 1.0 op_sel_hi:[1,0]
	v_pk_add_f32 v[62:63], v[62:63], 1.0 op_sel_hi:[1,0]
	v_rcp_f32_e32 v48, v48
	v_rcp_f32_e32 v49, v49
	v_rcp_f32_e32 v50, v50
	v_rcp_f32_e32 v51, v51
	v_rcp_f32_e32 v52, v52
	v_rcp_f32_e32 v53, v53
	v_rcp_f32_e32 v54, v54
	v_rcp_f32_e32 v55, v55
	v_rcp_f32_e32 v56, v56
	v_rcp_f32_e32 v57, v57
	v_rcp_f32_e32 v58, v58
	v_rcp_f32_e32 v59, v59
	v_rcp_f32_e32 v60, v60
	v_rcp_f32_e32 v61, v61
	v_rcp_f32_e32 v62, v62
	v_rcp_f32_e32 v63, v63
	s_waitcnt lgkmcnt(0)
; template <int dir>
; __device__ __forceinline__ void lru_pass(LAS unsigned char* lds, const Params& P, int b, int h, int q, bool dry) {
;     ...
;             for (int v = 0; v < 16; ++v) {
;                 const float xcv = __uint_as_float(xcb[v] << 16);
;                 const float r = __builtin_amdgcn_rcpf(1.0f + __builtin_amdgcn_exp2f(zr[v]));
;                 const float ig = __builtin_amdgcn_rcpf(1.0f + __builtin_amdgcn_exp2f(zi[v]));
;                 const float a = __builtin_amdgcn_exp2f(cl * r);
;                 const float sq = __builtin_amdgcn_sqrtf(fmaf(-a, a, 1.0f));
;                 const float u = sq * ig * xcv;
;                 E = fmaf(a, E, u); Pp *= a; zr[v] = E; zi[v] = Pp; }
;             const float Po = __shfl_xor(Pp, 32), Eo = __shfl_xor(E, 32);
;             const float P0 = g ? Po : Pp, E0 = g ? Eo : E, P1 = g ? Pp : Po, E1 = g ? E : Eo;
;             if (g == 0) { AGG[(wid * 2 + 0) * 32 + nl] = P0 * P1; AGG[(wid * 2 + 1) * 32 + nl] = fmaf(P1, E0, E1); }
	v_pk_fma_f32 v[244:245], v[32:33], v[32:33], 1.0 op_sel_hi:[1,1,0] neg_lo:[1,0,0] neg_hi:[1,0,0]
	v_pk_fma_f32 v[246:247], v[34:35], v[34:35], 1.0 op_sel_hi:[1,1,0] neg_lo:[1,0,0] neg_hi:[1,0,0]
	v_sqrt_f32_e32 v244, v244
	v_sqrt_f32_e32 v245, v245
	v_sqrt_f32_e32 v246, v246
	v_sqrt_f32_e32 v247, v247
	v_lshlrev_b32_e32 v162, 16, v162
	v_lshlrev_b32_e32 v163, 16, v163
	v_lshlrev_b32_e32 v232, 16, v232
	v_lshlrev_b32_e32 v233, 16, v233
	v_pk_mul_f32 v[244:245], v[244:245], v[48:49]
	v_pk_mul_f32 v[246:247], v[246:247], v[50:51]
	v_mul_f32_e32 v49, v244, v162
	v_mul_f32_e32 v228, v245, v163
	v_mul_f32_e32 v229, v246, v232
	v_mul_f32_e32 v230, v247, v233
	v_pk_fma_f32 v[244:245], v[36:37], v[36:37], 1.0 op_sel_hi:[1,1,0] neg_lo:[1,0,0] neg_hi:[1,0,0]
	v_pk_fma_f32 v[246:247], v[38:39], v[38:39], 1.0 op_sel_hi:[1,1,0] neg_lo:[1,0,0] neg_hi:[1,0,0]
	v_sqrt_f32_e32 v244, v244
	v_sqrt_f32_e32 v245, v245
	v_sqrt_f32_e32 v246, v246
	v_sqrt_f32_e32 v247, v247
	v_lshlrev_b32_e32 v234, 16, v234
	v_lshlrev_b32_e32 v235, 16, v235
	v_lshlrev_b32_e32 v236, 16, v236
	v_lshlrev_b32_e32 v237, 16, v237
	v_pk_mul_f32 v[244:245], v[244:245], v[52:53]
	v_pk_mul_f32 v[246:247], v[246:247], v[54:55]
	v_mul_f32_e32 v231, v244, v234
	v_mul_f32_e32 v232, v245, v235
	v_mul_f32_e32 v233, v246, v236
	v_mul_f32_e32 v234, v247, v237
	v_pk_fma_f32 v[244:245], v[40:41], v[40:41], 1.0 op_sel_hi:[1,1,0] neg_lo:[1,0,0] neg_hi:[1,0,0]
	v_pk_fma_f32 v[246:247], v[42:43], v[42:43], 1.0 op_sel_hi:[1,1,0] neg_lo:[1,0,0] neg_hi:[1,0,0]
	v_sqrt_f32_e32 v244, v244
	v_sqrt_f32_e32 v245, v245
	v_sqrt_f32_e32 v246, v246
	v_sqrt_f32_e32 v247, v247
	v_lshlrev_b32_e32 v146, 16, v146
	v_lshlrev_b32_e32 v147, 16, v147
	v_lshlrev_b32_e32 v148, 16, v148
	v_lshlrev_b32_e32 v149, 16, v149
	v_pk_mul_f32 v[244:245], v[244:245], v[56:57]
	v_pk_mul_f32 v[246:247], v[246:247], v[58:59]
	v_mul_f32_e32 v235, v244, v146
	v_mul_f32_e32 v236, v245, v147
	v_mul_f32_e32 v237, v246, v148
	v_mul_f32_e32 v238, v247, v149
	v_pk_fma_f32 v[244:245], v[44:45], v[44:45], 1.0 op_sel_hi:[1,1,0] neg_lo:[1,0,0] neg_hi:[1,0,0]
	v_pk_fma_f32 v[246:247], v[46:47], v[46:47], 1.0 op_sel_hi:[1,1,0] neg_lo:[1,0,0] neg_hi:[1,0,0]
	v_sqrt_f32_e32 v244, v244
	v_sqrt_f32_e32 v245, v245
	v_sqrt_f32_e32 v246, v246
	v_sqrt_f32_e32 v247, v247
	v_lshlrev_b32_e32 v239, 16, v239
	v_lshlrev_b32_e32 v240, 16, v240
	v_lshlrev_b32_e32 v241, 16, v241
	v_lshlrev_b32_e32 v242, 16, v242
	v_pk_mul_f32 v[244:245], v[244:245], v[60:61]
	v_pk_mul_f32 v[246:247], v[246:247], v[62:63]
	v_mul_f32_e32 v239, v244, v239
	v_mul_f32_e32 v240, v245, v240
	v_mul_f32_e32 v63, v246, v241
	v_mul_f32_e32 v241, v247, v242
	v_mov_b32_e32 v227, v32
	v_fmac_f32_e32 v49, 0, v32
	v_fmac_f32_e32 v228, v33, v49
	v_mul_f32_e32 v50, v227, v33
	v_fmac_f32_e32 v229, v34, v228
	v_mul_f32_e32 v51, v50, v34
	v_fmac_f32_e32 v230, v35, v229
	v_mul_f32_e32 v52, v51, v35
	v_fmac_f32_e32 v231, v36, v230
	v_mul_f32_e32 v53, v52, v36
	v_fmac_f32_e32 v232, v37, v231
	v_mul_f32_e32 v54, v53, v37
	v_fmac_f32_e32 v233, v38, v232
	v_mul_f32_e32 v55, v54, v38
	v_fmac_f32_e32 v234, v39, v233
	v_mul_f32_e32 v56, v55, v39
	v_fmac_f32_e32 v235, v40, v234
	v_mul_f32_e32 v57, v56, v40
	v_fmac_f32_e32 v236, v41, v235
	v_mul_f32_e32 v58, v57, v41
	v_fmac_f32_e32 v237, v42, v236
	v_mul_f32_e32 v59, v58, v42
	v_fmac_f32_e32 v238, v43, v237
	v_mul_f32_e32 v60, v59, v43
	v_fmac_f32_e32 v239, v44, v238
	v_mul_f32_e32 v61, v60, v44
	v_fmac_f32_e32 v240, v45, v239
	v_mul_f32_e32 v62, v61, v45
	v_fmac_f32_e32 v63, v46, v240
	v_mul_f32_e32 v243, v62, v46
	v_fmac_f32_e32 v241, v47, v63
	v_mul_f32_e32 v242, v243, v47
	v_mov_b32_e32 v244, v242
	v_mov_b32_e32 v246, v242
	v_mov_b32_e32 v245, v241
	v_mov_b32_e32 v247, v241
	s_nop 1
	v_permlane32_swap_b32 v244, v246
	v_permlane32_swap_b32 v245, v247
	s_and_saveexec_b64 s[18:19], vcc
	s_cbranch_execz .LBB0_313
	v_fma_f32 v32, v246, v245, v247
	v_mul_f32_e32 v33, v244, v246
	v_add_u32_e32 v35, s98, v254
	ds_write2_b32 v35, v33, v32 offset1:32
